# HG scan: conflict-free LDS layout + software-pipelined packed-f32 loop + transposed DPP reduction; MLA softmax pk ops split
# speedup vs baseline: 1.0441x; 1.0441x over previous
; #define PIN() do { asm volatile("" ::: "memory"); __builtin_amdgcn_sched_barrier(0); } while (0)
; #define MFMA(a, b, c) __builtin_amdgcn_mfma_f32_32x32x16_bf16((a), (b), (c), 0, 0, 0)
; DI unsigned pk2(float a, float b) { f32x2_t v = {a, b}; bf16x2_t r = __builtin_convertvector(v, bf16x2_t); return __builtin_bit_cast(unsigned, r); }
; #define VLD(dst_, s4_) do { _Pragma("unroll") for (int db = 0; db < 4; ++db) dst_[db].v = *(const bf16x8*)(vbase + db * 32 * VSTR + (s4_) * 32); } while (0)
; template <int DQK, int NM>
; DI void attn_item(const bf16_t* Qb, const bf16_t* Kb, size_t mstride, const bf16_t* VTb,
;                   int q0, int nkt, float cs, bf16_t* Orow  , float lam, float outscale, const float* subw, char* smem) {
;     ...
;     {
;       const f32x2_t cs2 = {cs, cs}, mc2 = {mrun * cs, mrun * cs};
;       f32x2_t ps2 = {0.f, 0.f};
; #pragma unroll
;       for (int kb = 0; kb < 2; ++kb)
; #pragma unroll
;         for (int i = 0; i < 16; i += 2) {
;           f32x2_t t = {sacc[kb][i], sacc[kb][i + 1]};
;           t = t * cs2 - mc2;
;           t.x = __builtin_amdgcn_exp2f(t.x); t.y = __builtin_amdgcn_exp2f(t.y);
;           sacc[kb][i] = t.x; sacc[kb][i + 1] = t.y;
;           ps2 = ps2 + t;
;         }
;       lrun += ps2.x + ps2.y;
;     }
;     const char* vbase = cur + KT_BYTES + l31 * VSTR + hh * 16;
;     {
;       struct VF { bf16x8 v; };
;       VF vfa[4], vfb[4];
;     ...
;       VLD(vfa, 0);
; #pragma unroll
;       for (int s4 = 0; s4 < 4; ++s4) {
;         const int kb = s4 >> 1, sp = s4 & 1;
;         PIN();
;         if (s4 < 3) { if (s4 & 1) VLD(vfa, s4 + 1); else VLD(vfb, s4 + 1); }
;         union { bf16x8 v; unsigned u[4]; } pf;
; #pragma unroll
;         for (int e = 0; e < 4; ++e) pf.u[e] = pk2(sacc[kb][8 * sp + 2 * e], sacc[kb][8 * sp + 2 * e + 1]);
;         PIN();
; #pragma unroll
;         for (int db = 0; db < 4; ++db) { if (s4 & 1) oacc[db] = MFMA(vfb[db].v, pf.v, oacc[db]); else oacc[db] = MFMA(vfa[db].v, pf.v, oacc[db]); }
;         {
;           char* b_ = smem + ((kt + 1) & 1) * BUF;
;           if (s4 == 0) { *(uint4*)(b_ + klo[0]) = kreg0; if (NKC > 2) *(uint4*)(b_ + klo[2]) = kreg2; }
;           if (s4 == 1) { *(uint4*)(b_ + klo[1]) = kreg1; }
;           if (s4 == 2) { *(uint4*)(b_ + vlo0) = vreg0; }
;           if (s4 == 3) { *(uint4*)(b_ + vlo1) = vreg1; }
;         }
;       }
.LBB0_126:
	v_mul_f32_e32 v196, 0x3dd53b95, v218
	v_fma_f32 v80, v80, s26, -v196
	v_fma_f32 v81, v81, s26, -v196
	v_fma_f32 v64, v64, s26, -v196
	v_fma_f32 v65, v65, s26, -v196
	v_exp_f32_e32 v220, v80
	v_exp_f32_e32 v221, v81
	v_fma_f32 v80, v82, s26, -v196
	v_fma_f32 v81, v83, s26, -v196
	v_fma_f32 v82, v88, s26, -v196
	v_fma_f32 v83, v89, s26, -v196
	v_exp_f32_e32 v222, v80
	v_exp_f32_e32 v223, v81
	v_fma_f32 v80, v84, s26, -v196
	v_fma_f32 v81, v85, s26, -v196
	v_exp_f32_e32 v228, v82
	v_exp_f32_e32 v224, v80
	v_exp_f32_e32 v225, v81
	v_fma_f32 v80, v86, s26, -v196
	v_fma_f32 v81, v87, s26, -v196
	v_exp_f32_e32 v229, v83
	v_exp_f32_e32 v226, v80
	v_exp_f32_e32 v227, v81
	v_add_f32_e64 v80, v220, 0
	v_add_f32_e64 v81, v221, 0
	v_fma_f32 v82, v90, s26, -v196
	v_fma_f32 v83, v91, s26, -v196
	v_add_f32_e64 v80, v222, v80
	v_add_f32_e64 v81, v223, v81
	v_exp_f32_e32 v230, v82
	v_exp_f32_e32 v231, v83
	v_fma_f32 v82, v92, s26, -v196
	v_fma_f32 v83, v93, s26, -v196
	v_add_f32_e64 v80, v224, v80
	v_add_f32_e64 v81, v225, v81
	v_exp_f32_e32 v232, v82
	v_exp_f32_e32 v233, v83
	v_fma_f32 v82, v94, s26, -v196
	v_fma_f32 v83, v95, s26, -v196
	v_add_f32_e64 v80, v226, v80
	v_add_f32_e64 v81, v227, v81
	v_exp_f32_e32 v234, v82
	v_exp_f32_e32 v235, v83
	v_add_f32_e64 v80, v228, v80
	v_add_f32_e64 v81, v229, v81
	v_exp_f32_e32 v236, v64
	v_exp_f32_e32 v237, v65
	v_fma_f32 v64, v66, s26, -v196
	v_fma_f32 v65, v67, s26, -v196
	v_add_f32_e64 v80, v230, v80
	v_add_f32_e64 v81, v231, v81
	v_exp_f32_e32 v238, v64
	v_exp_f32_e32 v239, v65
	v_fma_f32 v64, v68, s26, -v196
	v_fma_f32 v65, v69, s26, -v196
	v_add_f32_e64 v80, v232, v80
	v_add_f32_e64 v81, v233, v81
	v_exp_f32_e32 v240, v64
	v_exp_f32_e32 v241, v65
	v_fma_f32 v64, v70, s26, -v196
	v_fma_f32 v65, v71, s26, -v196
	v_add_f32_e64 v80, v234, v80
	v_add_f32_e64 v81, v235, v81
	v_exp_f32_e32 v242, v64
	v_exp_f32_e32 v243, v65
	v_fma_f32 v66, v72, s26, -v196
	v_fma_f32 v67, v73, s26, -v196
	v_add_f32_e64 v64, v236, v80
	v_add_f32_e64 v65, v237, v81
	v_exp_f32_e32 v244, v66
	v_exp_f32_e32 v245, v67
	v_fma_f32 v66, v74, s26, -v196
	v_fma_f32 v67, v75, s26, -v196
	v_add_f32_e64 v64, v238, v64
	v_add_f32_e64 v65, v239, v65
	v_exp_f32_e32 v246, v66
	v_exp_f32_e32 v247, v67
	v_fma_f32 v66, v76, s26, -v196
	v_fma_f32 v67, v77, s26, -v196
	v_add_f32_e64 v64, v240, v64
	v_add_f32_e64 v65, v241, v65
	v_exp_f32_e32 v248, v66
	v_exp_f32_e32 v249, v67
	v_fma_f32 v66, v78, s26, -v196
	v_fma_f32 v67, v79, s26, -v196
	v_add_f32_e64 v64, v242, v64
	v_add_f32_e64 v65, v243, v65
	v_exp_f32_e32 v250, v66
	v_exp_f32_e32 v251, v67
	v_add_f32_e64 v64, v244, v64
	v_add_f32_e64 v65, v245, v65
	v_add3_u32 v219, s25, v214, v170
	v_add_f32_e64 v64, v246, v64
	v_add_f32_e64 v65, v247, v65
	s_cmp_eq_u32 s24, 1
	v_add_f32_e64 v64, v248, v64
	v_add_f32_e64 v65, v249, v65
	s_cselect_b32 s24, 0xac00, 0
	v_add_f32_e64 v80, v250, v64
	v_add_f32_e64 v81, v251, v65
	ds_read_b128 v[64:67], v219 offset:25600
	ds_read_b128 v[68:71], v219 offset:30208
	ds_read_b128 v[72:75], v219 offset:34816
	ds_read_b128 v[76:79], v219 offset:39424
	s_add_i32 s24, s24, 0
	v_add_f32_e32 v203, v80, v81
	v_add_u32_e32 v206, s24, v197
	v_add_u32_e32 v211, s24, v216
	ds_read_b128 v[80:83], v219 offset:25632
	ds_read_b128 v[84:87], v219 offset:30240
	ds_read_b128 v[88:91], v219 offset:34848
	ds_read_b128 v[92:95], v219 offset:39456
	v_cvt_pk_bf16_f32 v220, v220, v221
	v_cvt_pk_bf16_f32 v221, v222, v223
	v_cvt_pk_bf16_f32 v222, v224, v225
	v_cvt_pk_bf16_f32 v223, v226, v227
	s_waitcnt lgkmcnt(7)
	s_nop 0
	v_mfma_f32_32x32x16_bf16 v[32:47], v[64:67], v[220:223], v[32:47]
	s_waitcnt vmcnt(4)
	ds_write_b128 v206, v[158:161]
	s_waitcnt vmcnt(2)
	ds_write_b128 v211, v[162:165]
	s_waitcnt lgkmcnt(8)
	v_mfma_f32_32x32x16_bf16 v[48:63], v[68:71], v[220:223], v[48:63]
	s_waitcnt lgkmcnt(7)
	v_mfma_f32_32x32x16_bf16 v[16:31], v[72:75], v[220:223], v[16:31]
	s_waitcnt lgkmcnt(6)
	v_mfma_f32_32x32x16_bf16 v[0:15], v[76:79], v[220:223], v[0:15]
	ds_read_b128 v[64:67], v219 offset:25664
	ds_read_b128 v[68:71], v219 offset:30272
	ds_read_b128 v[72:75], v219 offset:34880
	ds_read_b128 v[76:79], v219 offset:39488
	v_cvt_pk_bf16_f32 v158, v228, v229
	v_cvt_pk_bf16_f32 v159, v230, v231
	v_cvt_pk_bf16_f32 v160, v232, v233
	v_cvt_pk_bf16_f32 v161, v234, v235
	s_waitcnt lgkmcnt(9)
	s_nop 0
	v_mfma_f32_32x32x16_bf16 v[32:47], v[80:83], v[158:161], v[32:47]
	v_add_u32_e32 v80, s24, v215
	ds_write_b128 v80, v[154:157]
	s_waitcnt lgkmcnt(9)
	v_mfma_f32_32x32x16_bf16 v[48:63], v[84:87], v[158:161], v[48:63]
	s_waitcnt lgkmcnt(8)
	v_mfma_f32_32x32x16_bf16 v[16:31], v[88:91], v[158:161], v[16:31]
	s_waitcnt lgkmcnt(7)
	v_mfma_f32_32x32x16_bf16 v[0:15], v[92:95], v[158:161], v[0:15]
	ds_read_b128 v[80:83], v219 offset:25696
	ds_read_b128 v[84:87], v219 offset:30304
	ds_read_b128 v[88:91], v219 offset:34912
	ds_read_b128 v[92:95], v219 offset:39520
	v_cvt_pk_bf16_f32 v154, v236, v237
	v_cvt_pk_bf16_f32 v155, v238, v239
	v_cvt_pk_bf16_f32 v156, v240, v241
	v_cvt_pk_bf16_f32 v157, v242, v243
	s_waitcnt lgkmcnt(8)
	s_nop 0
	v_mfma_f32_32x32x16_bf16 v[32:47], v[64:67], v[154:157], v[32:47]
	v_add_u32_e32 v64, s24, v182
	s_waitcnt vmcnt(1)
	ds_write_b128 v64, v[150:153] offset:25600
	s_waitcnt lgkmcnt(8)
	v_mfma_f32_32x32x16_bf16 v[48:63], v[68:71], v[154:157], v[48:63]
	s_waitcnt lgkmcnt(7)
	v_mfma_f32_32x32x16_bf16 v[16:31], v[72:75], v[154:157], v[16:31]
	s_waitcnt lgkmcnt(6)
	v_mfma_f32_32x32x16_bf16 v[0:15], v[76:79], v[154:157], v[0:15]
	v_cvt_pk_bf16_f32 v64, v244, v245
	v_cvt_pk_bf16_f32 v65, v246, v247
	v_cvt_pk_bf16_f32 v66, v248, v249
	v_cvt_pk_bf16_f32 v67, v250, v251
	s_waitcnt lgkmcnt(4)
	s_nop 0
	v_mfma_f32_32x32x16_bf16 v[32:47], v[80:83], v[64:67], v[32:47]
	v_add_u32_e32 v68, s24, v184
	s_waitcnt vmcnt(0)
	ds_write_b128 v68, v[146:149] offset:25600
	v_add_f32_e32 v185, v185, v203
	s_waitcnt lgkmcnt(4)
	v_mfma_f32_32x32x16_bf16 v[48:63], v[84:87], v[64:67], v[48:63]
	s_waitcnt lgkmcnt(3)
	v_mfma_f32_32x32x16_bf16 v[16:31], v[88:91], v[64:67], v[16:31]
	s_waitcnt lgkmcnt(2)
	v_mfma_f32_32x32x16_bf16 v[0:15], v[92:95], v[64:67], v[0:15]
	s_mov_b64 s[34:35], 0x80
	s_add_i32 s37, s37, 1
	v_lshl_add_u64 v[186:187], v[186:187], 0, s[34:35]
	v_lshl_add_u64 v[188:189], v[188:189], 0, s[34:35]
	s_mov_b64 s[34:35], 0x6000
	v_lshl_add_u64 v[190:191], v[190:191], 0, s[34:35]
	v_lshl_add_u64 v[192:193], v[192:193], 0, s[34:35]
	s_cmpk_eq_i32 s37, 0x84
	v_lshl_add_u64 v[194:195], v[194:195], 0, s[34:35]
	s_waitcnt lgkmcnt(0)
	s_barrier
	s_cbranch_scc1 .LBB0_129

; DI int TID() { int t = threadIdx.x; asm volatile("" : "+v"(t)); return t; }
; DI int BID() { int t = blockIdx.x; asm volatile("" : "+s"(t)); return t; }
; DI void phase_hg_scan(const Params& p, char* smem) {
;   const int tid = TID(), lane = tid & 63, wv = tid >> 6;
;   const int dpart = lane & 15, esub = lane >> 4, el = wv * 4 + esub;
;   const bf16_t* qb = (const bf16_t*)(p.ws + HG_Q);
;   const bf16_t* ib = (const bf16_t*)(p.ws + HG_I);
;   const int ltok = tid >> 4, ldc = tid & 15;
;   const int vtok = (tid & 127) >> 2, vec = tid & 3;
;   for (int item = BID(); item < 256; item += gridDim.x) {
;     const int b = item >> 6, h = (item >> 3) & 7, dir = (item >> 2) & 1, eq = item & 3;
;     const bf16_t* kk = (const bf16_t*)(p.ws + (dir ? HG_KB : HG_KF));
;     bf16_t* oo = (bf16_t*)(p.ws + (dir ? HG_OB : OFF_ABUF));
;     const size_t rowbase = (size_t)b * PL;
;     const int colq = h * 128 + ldc * 8, colv = h * 128 + eq * 32 + vec * 8, colo = h * 128 + eq * 32 + el;
;     auto posf = [&](int tau) { return dir ? (tau < CTXL ? CTXL - 1 - tau : PL - 1 - (tau - CTXL)) : tau; };
;     f32x2_t S[4];
; #pragma unroll
;     for (int j = 0; j < 4; ++j) S[j] = f32x2_t{0.f, 0.f};
;     uint4 aq, ak, av, bq, bk, bv;
;     av = make_uint4(0, 0, 0, 0); bv = av;
.LBB0_190:
	s_cmp_eq_u32 s12, 1
	s_mov_b64 s[0:1], -1
	s_cbranch_scc0 .LBB0_251
	v_writelane_b32 v255, s52, 6
	s_waitcnt vmcnt(1)
	v_mov_b32_e32 v0, v167
	s_mov_b32 s96, s50
	v_writelane_b32 v255, s53, 7
	v_writelane_b32 v255, s50, 8
	s_cmpk_gt_i32 s96, 0xff
	s_cbranch_scc1 .LBB0_250
	v_lshlrev_b32_e32 v2, 3, v0
	s_movk_i32 s0, 0x80
	v_lshrrev_b32_e32 v1, 4, v0
	v_ashrrev_i32_e32 v58, 4, v0
	v_and_b32_e32 v61, 0x78, v2
	v_cmp_gt_i32_e64 s[38:39], s0, v0
	s_movk_i32 s0, 0x7f
	v_and_b32_e32 v57, 15, v0
	v_bfi_b32 v59, -4, v58, v1
	v_lshrrev_b32_e32 v1, 2, v0
	v_bfe_u32 v60, v0, 2, 5
	v_and_b32_e32 v62, 24, v2
	v_cmp_lt_i32_e64 s[0:1], s0, v0
	v_lshlrev_b32_e32 v0, 9, v58
	v_lshlrev_b32_e32 v2, 1, v61
	v_writelane_b32 v255, s0, 9
	v_add3_u32 v64, 0, v0, v2
	v_lshlrev_b32_e32 v2, 2, v62
	v_writelane_b32 v255, s1, 10
	s_movk_i32 s3, 0xff
	v_lshlrev_b32_e32 v0, 7, v60
	v_add_u32_e32 v3, 0, v2
	s_movk_i32 s1, 0xdf
	s_add_i32 s0, 0, 0x11000
	v_bitop3_b32 v63, v1, s3, 31 bitop3:0x6c
	v_add_u32_e32 v65, v3, v0
	v_bitop3_b32 v68, v1, s1, 31 bitop3:0x6c
	v_add_u32_e32 v1, s0, v2
	v_cmp_lt_i32_e32 vcc, s3, v58
	v_mov_b32_e32 v2, 0xff
	v_mov_b32_e32 v3, 0x21ff
	v_cndmask_b32_e32 v2, v2, v3, vcc
	v_sub_u32_e32 v70, v2, v58
	v_cmp_lt_i32_e32 vcc, s1, v58
	v_mov_b32_e32 v2, 0xdf
	v_mov_b32_e32 v3, 0x21df
	v_cndmask_b32_e32 v2, v2, v3, vcc
	v_writelane_b32 v255, s74, 11
	v_add_u32_e32 v66, 32, v58
	v_or_b32_e32 v67, 32, v60
	v_lshl_add_u32 v69, v57, 4, 0
	v_sub_u32_e32 v71, v2, v58
	v_and_b32_e32 v110, 2, v57
	v_cmp_eq_u32_e64 s[42:43], 0, v110
	v_and_b32_e32 v111, 1, v57
	v_cmp_eq_u32_e64 s[44:45], 0, v111
	v_cmp_eq_u32_e64 s[46:47], 2, v57
	v_cmp_eq_u32_e64 s[48:49], 3, v57
	v_cmp_eq_u32_e64 s[50:51], 4, v57
	v_cmp_eq_u32_e64 s[52:53], 5, v57
	v_cmp_eq_u32_e64 s[54:55], 6, v57
	v_cmp_eq_u32_e64 s[56:57], 7, v57
	v_cmp_eq_u32_e64 s[58:59], 8, v57
	v_cmp_eq_u32_e64 s[60:61], 9, v57
	v_cmp_eq_u32_e64 s[62:63], 10, v57
	v_cmp_eq_u32_e64 s[64:65], 11, v57
	v_cmp_eq_u32_e64 s[66:67], 12, v57
	v_cmp_eq_u32_e64 s[68:69], 13, v57
	v_cmp_eq_u32_e64 s[70:71], 14, v57
	v_cmp_eq_u32_e64 s[72:73], 15, v57
	v_lshl_add_u32 v72, v59, 2, 0
	v_add_u32_e32 v73, v1, v0
	v_writelane_b32 v255, s75, 12
	s_branch .LBB0_194

.LBB0_196:
	s_or_b64 exec, exec, s[30:31]
	s_waitcnt vmcnt(1)
	v_lshlrev_b32_e32 v16, 16, v9
	v_lshlrev_b32_e32 v14, 16, v8
	v_lshlrev_b32_e32 v20, 16, v11
	v_lshlrev_b32_e32 v18, 16, v10
	v_and_b32_e32 v17, 0xffff0000, v9
	v_and_b32_e32 v15, 0xffff0000, v8
	v_and_b32_e32 v21, 0xffff0000, v11
	v_and_b32_e32 v19, 0xffff0000, v10
	ds_write_b128 v64, v[18:21] offset:256
	ds_write_b128 v64, v[14:17]
	s_waitcnt vmcnt(0)
	v_lshlrev_b32_e32 v16, 16, v7
	v_lshlrev_b32_e32 v14, 16, v6
	v_and_b32_e32 v17, 0xffff0000, v7
	v_and_b32_e32 v15, 0xffff0000, v6
	v_lshlrev_b32_e32 v10, 16, v5
	v_lshlrev_b32_e32 v8, 16, v4
	v_and_b32_e32 v11, 0xffff0000, v5
	v_and_b32_e32 v9, 0xffff0000, v4
	ds_write_b128 v64, v[14:17] offset:16640
	ds_write_b128 v64, v[8:11] offset:16384
	s_and_saveexec_b64 s[30:31], s[38:39]
	s_cbranch_execz .LBB0_198
	v_lshlrev_b32_e32 v4, 16, v0
	v_and_b32_e32 v5, 0xffff0000, v0
	v_lshlrev_b32_e32 v6, 16, v1
	v_and_b32_e32 v7, 0xffff0000, v1
	v_lshlrev_b32_e32 v8, 16, v2
	v_and_b32_e32 v9, 0xffff0000, v2
	v_lshlrev_b32_e32 v10, 16, v3
	v_and_b32_e32 v11, 0xffff0000, v3
	ds_write_b128 v65, v[4:7] offset:32768
	ds_write_b128 v65, v[8:11] offset:32784

.LBB0_218:
	v_cvt_pk_bf16_f32 v27, v25, s0
	v_ashrrev_i32_e32 v25, 31, v24
	v_lshl_add_u64 v[24:25], s[40:41], 0, v[24:25]
	s_xor_b64 s[36:37], s[30:31], -1
	v_lshlrev_b64 v[24:25], 11, v[24:25]
	v_lshl_add_u64 v[24:25], v[46:47], 0, v[24:25]
	s_mov_b32 s25, 16
	s_mov_b64 s[30:31], 0
	s_and_b64 vcc, exec, s[36:37]
	global_store_short v[24:25], v27, off
	s_cbranch_vccnz .LBB0_224
.LBB0_219:
	v_lshl_add_u32 v188, s25, 9, v69
	v_lshl_add_u32 v189, s25, 7, v72
	v_add_u32_e32 v190, 0x8400, v189
	v_add_u32_e32 v189, 0x8000, v189
	ds_read2_b32 v[172:173], v189 offset1:32
	ds_read2_b32 v[174:175], v189 offset0:64 offset1:96
	ds_read2_b32 v[176:177], v189 offset0:128 offset1:160
	ds_read2_b32 v[178:179], v189 offset0:192 offset1:224
	ds_read_b128 v[120:123], v188 offset:16384
	ds_read_b128 v[124:127], v188 offset:16640
	ds_read_b128 v[112:115], v188 offset:0
	ds_read_b128 v[116:119], v188 offset:256
	ds_read_b128 v[136:139], v188 offset:16896
	ds_read_b128 v[144:147], v188 offset:17152
	ds_read_b128 v[156:159], v188 offset:17408
	ds_read_b128 v[168:171], v188 offset:17664
	ds_read_b128 v[128:131], v188 offset:512
	ds_read_b128 v[132:135], v188 offset:768
	s_waitcnt lgkmcnt(8)
	v_pk_add_f32 v[230:231], v[172:173], v[36:37] op_sel_hi:[0,1] neg_lo:[0,1] neg_hi:[0,1]
	v_pk_add_f32 v[232:233], v[172:173], v[48:49] op_sel_hi:[0,1] neg_lo:[0,1] neg_hi:[0,1]
	v_pk_add_f32 v[234:235], v[172:173], v[38:39] op_sel_hi:[0,1] neg_lo:[0,1] neg_hi:[0,1]
	v_pk_add_f32 v[236:237], v[172:173], v[32:33] op_sel_hi:[0,1] neg_lo:[0,1] neg_hi:[0,1]
	v_pk_fma_f32 v[244:245], v[120:121], v[230:231], v[36:37]
	v_pk_fma_f32 v[246:247], v[122:123], v[232:233], v[48:49]
	v_pk_fma_f32 v[248:249], v[124:125], v[234:235], v[38:39]
	v_pk_fma_f32 v[250:251], v[126:127], v[236:237], v[32:33]
	ds_read_b128 v[120:123], v188 offset:17920
	ds_read_b128 v[124:127], v188 offset:18176
	ds_read_b128 v[148:151], v188 offset:1024
	ds_read_b128 v[152:155], v188 offset:1280
	s_waitcnt lgkmcnt(8)
	v_pk_add_f32 v[230:231], v[172:173], v[244:245] op_sel:[1,0] op_sel_hi:[1,1] neg_lo:[0,1] neg_hi:[0,1]
	v_pk_add_f32 v[232:233], v[172:173], v[246:247] op_sel:[1,0] op_sel_hi:[1,1] neg_lo:[0,1] neg_hi:[0,1]
	v_pk_add_f32 v[234:235], v[172:173], v[248:249] op_sel:[1,0] op_sel_hi:[1,1] neg_lo:[0,1] neg_hi:[0,1]
	v_pk_add_f32 v[236:237], v[172:173], v[250:251] op_sel:[1,0] op_sel_hi:[1,1] neg_lo:[0,1] neg_hi:[0,1]
	v_pk_fma_f32 v[36:37], v[136:137], v[230:231], v[244:245]
	v_pk_mul_f32 v[238:239], v[114:115], v[246:247]
	v_pk_fma_f32 v[48:49], v[138:139], v[232:233], v[246:247]
	v_pk_fma_f32 v[238:239], v[112:113], v[244:245], v[238:239]
	v_pk_fma_f32 v[38:39], v[144:145], v[234:235], v[248:249]
	v_pk_fma_f32 v[238:239], v[116:117], v[248:249], v[238:239]
	v_pk_fma_f32 v[32:33], v[146:147], v[236:237], v[250:251]
	v_pk_fma_f32 v[238:239], v[118:119], v[250:251], v[238:239]
	ds_read_b128 v[136:139], v188 offset:18432
	ds_read_b128 v[144:147], v188 offset:18688
	ds_read_b128 v[112:115], v188 offset:1536
	ds_read_b128 v[116:119], v188 offset:1792
	s_waitcnt lgkmcnt(8)
	v_pk_add_f32 v[230:231], v[174:175], v[36:37] op_sel_hi:[0,1] neg_lo:[0,1] neg_hi:[0,1]
	v_pk_add_f32 v[232:233], v[174:175], v[48:49] op_sel_hi:[0,1] neg_lo:[0,1] neg_hi:[0,1]
	v_pk_add_f32 v[234:235], v[174:175], v[38:39] op_sel_hi:[0,1] neg_lo:[0,1] neg_hi:[0,1]
	v_pk_add_f32 v[236:237], v[174:175], v[32:33] op_sel_hi:[0,1] neg_lo:[0,1] neg_hi:[0,1]
	v_add_f32_e32 v214, v238, v239
	v_pk_fma_f32 v[244:245], v[156:157], v[230:231], v[36:37]
	v_pk_mul_f32 v[240:241], v[130:131], v[48:49]
	v_pk_fma_f32 v[246:247], v[158:159], v[232:233], v[48:49]
	v_pk_fma_f32 v[240:241], v[128:129], v[36:37], v[240:241]
	v_pk_fma_f32 v[248:249], v[168:169], v[234:235], v[38:39]
	v_pk_fma_f32 v[240:241], v[132:133], v[38:39], v[240:241]
	v_pk_fma_f32 v[250:251], v[170:171], v[236:237], v[32:33]
	v_pk_fma_f32 v[240:241], v[134:135], v[32:33], v[240:241]
	ds_read_b128 v[156:159], v188 offset:18944
	ds_read_b128 v[168:171], v188 offset:19200
	ds_read_b128 v[128:131], v188 offset:2048
	ds_read_b128 v[132:135], v188 offset:2304
	s_waitcnt lgkmcnt(8)
	v_pk_add_f32 v[230:231], v[174:175], v[244:245] op_sel:[1,0] op_sel_hi:[1,1] neg_lo:[0,1] neg_hi:[0,1]
	v_pk_add_f32 v[232:233], v[174:175], v[246:247] op_sel:[1,0] op_sel_hi:[1,1] neg_lo:[0,1] neg_hi:[0,1]
	v_pk_add_f32 v[234:235], v[174:175], v[248:249] op_sel:[1,0] op_sel_hi:[1,1] neg_lo:[0,1] neg_hi:[0,1]
	v_pk_add_f32 v[236:237], v[174:175], v[250:251] op_sel:[1,0] op_sel_hi:[1,1] neg_lo:[0,1] neg_hi:[0,1]
	v_add_f32_e32 v215, v240, v241
	v_pk_fma_f32 v[36:37], v[120:121], v[230:231], v[244:245]
	v_pk_mul_f32 v[238:239], v[150:151], v[246:247]
	v_pk_fma_f32 v[48:49], v[122:123], v[232:233], v[246:247]
	v_pk_fma_f32 v[238:239], v[148:149], v[244:245], v[238:239]
	v_pk_fma_f32 v[38:39], v[124:125], v[234:235], v[248:249]
	v_pk_fma_f32 v[238:239], v[152:153], v[248:249], v[238:239]
	v_pk_fma_f32 v[32:33], v[126:127], v[236:237], v[250:251]
	v_pk_fma_f32 v[238:239], v[154:155], v[250:251], v[238:239]
	ds_read_b128 v[120:123], v188 offset:19456
	ds_read_b128 v[124:127], v188 offset:19712
	ds_read_b128 v[148:151], v188 offset:2560
	ds_read_b128 v[152:155], v188 offset:2816
	ds_read2_b32 v[180:181], v190 offset1:32
	ds_read2_b32 v[182:183], v190 offset0:64 offset1:96
	ds_read2_b32 v[184:185], v190 offset0:128 offset1:160
	ds_read2_b32 v[186:187], v190 offset0:192 offset1:224
	s_waitcnt lgkmcnt(12)
	v_pk_add_f32 v[230:231], v[176:177], v[36:37] op_sel_hi:[0,1] neg_lo:[0,1] neg_hi:[0,1]
	v_pk_add_f32 v[232:233], v[176:177], v[48:49] op_sel_hi:[0,1] neg_lo:[0,1] neg_hi:[0,1]
	v_pk_add_f32 v[234:235], v[176:177], v[38:39] op_sel_hi:[0,1] neg_lo:[0,1] neg_hi:[0,1]
	v_pk_add_f32 v[236:237], v[176:177], v[32:33] op_sel_hi:[0,1] neg_lo:[0,1] neg_hi:[0,1]
	v_add_f32_e32 v216, v238, v239
	v_pk_fma_f32 v[244:245], v[136:137], v[230:231], v[36:37]
	v_pk_mul_f32 v[240:241], v[114:115], v[48:49]
	v_pk_fma_f32 v[246:247], v[138:139], v[232:233], v[48:49]
	v_pk_fma_f32 v[240:241], v[112:113], v[36:37], v[240:241]
	v_pk_fma_f32 v[248:249], v[144:145], v[234:235], v[38:39]
	v_pk_fma_f32 v[240:241], v[116:117], v[38:39], v[240:241]
	v_pk_fma_f32 v[250:251], v[146:147], v[236:237], v[32:33]
	v_pk_fma_f32 v[240:241], v[118:119], v[32:33], v[240:241]
	ds_read_b128 v[136:139], v188 offset:19968
	ds_read_b128 v[144:147], v188 offset:20224
	ds_read_b128 v[112:115], v188 offset:3072
	ds_read_b128 v[116:119], v188 offset:3328
	s_waitcnt lgkmcnt(12)
	v_pk_add_f32 v[230:231], v[176:177], v[244:245] op_sel:[1,0] op_sel_hi:[1,1] neg_lo:[0,1] neg_hi:[0,1]
	v_pk_add_f32 v[232:233], v[176:177], v[246:247] op_sel:[1,0] op_sel_hi:[1,1] neg_lo:[0,1] neg_hi:[0,1]
	v_pk_add_f32 v[234:235], v[176:177], v[248:249] op_sel:[1,0] op_sel_hi:[1,1] neg_lo:[0,1] neg_hi:[0,1]
	v_pk_add_f32 v[236:237], v[176:177], v[250:251] op_sel:[1,0] op_sel_hi:[1,1] neg_lo:[0,1] neg_hi:[0,1]
	v_add_f32_e32 v217, v240, v241
	v_pk_fma_f32 v[36:37], v[156:157], v[230:231], v[244:245]
	v_pk_mul_f32 v[238:239], v[130:131], v[246:247]
	v_pk_fma_f32 v[48:49], v[158:159], v[232:233], v[246:247]
	v_pk_fma_f32 v[238:239], v[128:129], v[244:245], v[238:239]
	v_pk_fma_f32 v[38:39], v[168:169], v[234:235], v[248:249]
	v_pk_fma_f32 v[238:239], v[132:133], v[248:249], v[238:239]
	v_pk_fma_f32 v[32:33], v[170:171], v[236:237], v[250:251]
	v_pk_fma_f32 v[238:239], v[134:135], v[250:251], v[238:239]
	ds_read_b128 v[156:159], v188 offset:20480
	ds_read_b128 v[168:171], v188 offset:20736
	ds_read_b128 v[128:131], v188 offset:3584
	ds_read_b128 v[132:135], v188 offset:3840
	s_waitcnt lgkmcnt(12)
	v_pk_add_f32 v[230:231], v[178:179], v[36:37] op_sel_hi:[0,1] neg_lo:[0,1] neg_hi:[0,1]
	v_pk_add_f32 v[232:233], v[178:179], v[48:49] op_sel_hi:[0,1] neg_lo:[0,1] neg_hi:[0,1]
	v_pk_add_f32 v[234:235], v[178:179], v[38:39] op_sel_hi:[0,1] neg_lo:[0,1] neg_hi:[0,1]
	v_pk_add_f32 v[236:237], v[178:179], v[32:33] op_sel_hi:[0,1] neg_lo:[0,1] neg_hi:[0,1]
	v_add_f32_e32 v218, v238, v239
	v_pk_fma_f32 v[244:245], v[120:121], v[230:231], v[36:37]
	v_pk_mul_f32 v[240:241], v[150:151], v[48:49]
	v_pk_fma_f32 v[246:247], v[122:123], v[232:233], v[48:49]
	v_pk_fma_f32 v[240:241], v[148:149], v[36:37], v[240:241]
	v_pk_fma_f32 v[248:249], v[124:125], v[234:235], v[38:39]
	v_pk_fma_f32 v[240:241], v[152:153], v[38:39], v[240:241]
	v_pk_fma_f32 v[250:251], v[126:127], v[236:237], v[32:33]
	v_pk_fma_f32 v[240:241], v[154:155], v[32:33], v[240:241]
	ds_read_b128 v[120:123], v188 offset:20992
	ds_read_b128 v[124:127], v188 offset:21248
	ds_read_b128 v[148:151], v188 offset:4096
	ds_read_b128 v[152:155], v188 offset:4352
	s_waitcnt lgkmcnt(8)
	v_pk_add_f32 v[230:231], v[178:179], v[244:245] op_sel:[1,0] op_sel_hi:[1,1] neg_lo:[0,1] neg_hi:[0,1]
	v_pk_add_f32 v[232:233], v[178:179], v[246:247] op_sel:[1,0] op_sel_hi:[1,1] neg_lo:[0,1] neg_hi:[0,1]
	v_pk_add_f32 v[234:235], v[178:179], v[248:249] op_sel:[1,0] op_sel_hi:[1,1] neg_lo:[0,1] neg_hi:[0,1]
	v_pk_add_f32 v[236:237], v[178:179], v[250:251] op_sel:[1,0] op_sel_hi:[1,1] neg_lo:[0,1] neg_hi:[0,1]
	v_add_f32_e32 v219, v240, v241
	v_pk_fma_f32 v[36:37], v[136:137], v[230:231], v[244:245]
	v_pk_mul_f32 v[238:239], v[114:115], v[246:247]
	v_pk_fma_f32 v[48:49], v[138:139], v[232:233], v[246:247]
	v_pk_fma_f32 v[238:239], v[112:113], v[244:245], v[238:239]
	v_pk_fma_f32 v[38:39], v[144:145], v[234:235], v[248:249]
	v_pk_fma_f32 v[238:239], v[116:117], v[248:249], v[238:239]
	v_pk_fma_f32 v[32:33], v[146:147], v[236:237], v[250:251]
	v_pk_fma_f32 v[238:239], v[118:119], v[250:251], v[238:239]
	ds_read_b128 v[136:139], v188 offset:21504
	ds_read_b128 v[144:147], v188 offset:21760
	ds_read_b128 v[112:115], v188 offset:4608
	ds_read_b128 v[116:119], v188 offset:4864
	s_waitcnt lgkmcnt(8)
	v_pk_add_f32 v[230:231], v[180:181], v[36:37] op_sel_hi:[0,1] neg_lo:[0,1] neg_hi:[0,1]
	v_pk_add_f32 v[232:233], v[180:181], v[48:49] op_sel_hi:[0,1] neg_lo:[0,1] neg_hi:[0,1]
	v_pk_add_f32 v[234:235], v[180:181], v[38:39] op_sel_hi:[0,1] neg_lo:[0,1] neg_hi:[0,1]
	v_pk_add_f32 v[236:237], v[180:181], v[32:33] op_sel_hi:[0,1] neg_lo:[0,1] neg_hi:[0,1]
	v_add_f32_e32 v220, v238, v239
	v_pk_fma_f32 v[244:245], v[156:157], v[230:231], v[36:37]
	v_pk_mul_f32 v[240:241], v[130:131], v[48:49]
	v_pk_fma_f32 v[246:247], v[158:159], v[232:233], v[48:49]
	v_pk_fma_f32 v[240:241], v[128:129], v[36:37], v[240:241]
	v_pk_fma_f32 v[248:249], v[168:169], v[234:235], v[38:39]
	v_pk_fma_f32 v[240:241], v[132:133], v[38:39], v[240:241]
	v_pk_fma_f32 v[250:251], v[170:171], v[236:237], v[32:33]
	v_pk_fma_f32 v[240:241], v[134:135], v[32:33], v[240:241]
	ds_read_b128 v[156:159], v188 offset:22016
	ds_read_b128 v[168:171], v188 offset:22272
	ds_read_b128 v[128:131], v188 offset:5120
	ds_read_b128 v[132:135], v188 offset:5376
	s_waitcnt lgkmcnt(8)
	v_pk_add_f32 v[230:231], v[180:181], v[244:245] op_sel:[1,0] op_sel_hi:[1,1] neg_lo:[0,1] neg_hi:[0,1]
	v_pk_add_f32 v[232:233], v[180:181], v[246:247] op_sel:[1,0] op_sel_hi:[1,1] neg_lo:[0,1] neg_hi:[0,1]
	v_pk_add_f32 v[234:235], v[180:181], v[248:249] op_sel:[1,0] op_sel_hi:[1,1] neg_lo:[0,1] neg_hi:[0,1]
	v_pk_add_f32 v[236:237], v[180:181], v[250:251] op_sel:[1,0] op_sel_hi:[1,1] neg_lo:[0,1] neg_hi:[0,1]
	v_add_f32_e32 v221, v240, v241
	v_pk_fma_f32 v[36:37], v[120:121], v[230:231], v[244:245]
	v_pk_mul_f32 v[238:239], v[150:151], v[246:247]
	v_pk_fma_f32 v[48:49], v[122:123], v[232:233], v[246:247]
	v_pk_fma_f32 v[238:239], v[148:149], v[244:245], v[238:239]
	v_pk_fma_f32 v[38:39], v[124:125], v[234:235], v[248:249]
	v_pk_fma_f32 v[238:239], v[152:153], v[248:249], v[238:239]
	v_pk_fma_f32 v[32:33], v[126:127], v[236:237], v[250:251]
	v_pk_fma_f32 v[238:239], v[154:155], v[250:251], v[238:239]
	ds_read_b128 v[120:123], v188 offset:22528
	ds_read_b128 v[124:127], v188 offset:22784
	ds_read_b128 v[148:151], v188 offset:5632
	ds_read_b128 v[152:155], v188 offset:5888
	s_waitcnt lgkmcnt(8)
	v_pk_add_f32 v[230:231], v[182:183], v[36:37] op_sel_hi:[0,1] neg_lo:[0,1] neg_hi:[0,1]
	v_pk_add_f32 v[232:233], v[182:183], v[48:49] op_sel_hi:[0,1] neg_lo:[0,1] neg_hi:[0,1]
	v_pk_add_f32 v[234:235], v[182:183], v[38:39] op_sel_hi:[0,1] neg_lo:[0,1] neg_hi:[0,1]
	v_pk_add_f32 v[236:237], v[182:183], v[32:33] op_sel_hi:[0,1] neg_lo:[0,1] neg_hi:[0,1]
	v_add_f32_e32 v222, v238, v239
	v_pk_fma_f32 v[244:245], v[136:137], v[230:231], v[36:37]
	v_pk_mul_f32 v[240:241], v[114:115], v[48:49]
	v_pk_fma_f32 v[246:247], v[138:139], v[232:233], v[48:49]
	v_pk_fma_f32 v[240:241], v[112:113], v[36:37], v[240:241]
	v_pk_fma_f32 v[248:249], v[144:145], v[234:235], v[38:39]
	v_pk_fma_f32 v[240:241], v[116:117], v[38:39], v[240:241]
	v_pk_fma_f32 v[250:251], v[146:147], v[236:237], v[32:33]
	v_pk_fma_f32 v[240:241], v[118:119], v[32:33], v[240:241]
	ds_read_b128 v[136:139], v188 offset:23040
	ds_read_b128 v[144:147], v188 offset:23296
	ds_read_b128 v[112:115], v188 offset:6144
	ds_read_b128 v[116:119], v188 offset:6400
	s_waitcnt lgkmcnt(8)
	v_pk_add_f32 v[230:231], v[182:183], v[244:245] op_sel:[1,0] op_sel_hi:[1,1] neg_lo:[0,1] neg_hi:[0,1]
	v_pk_add_f32 v[232:233], v[182:183], v[246:247] op_sel:[1,0] op_sel_hi:[1,1] neg_lo:[0,1] neg_hi:[0,1]
	v_pk_add_f32 v[234:235], v[182:183], v[248:249] op_sel:[1,0] op_sel_hi:[1,1] neg_lo:[0,1] neg_hi:[0,1]
	v_pk_add_f32 v[236:237], v[182:183], v[250:251] op_sel:[1,0] op_sel_hi:[1,1] neg_lo:[0,1] neg_hi:[0,1]
	v_add_f32_e32 v223, v240, v241
	v_pk_fma_f32 v[36:37], v[156:157], v[230:231], v[244:245]
	v_pk_mul_f32 v[238:239], v[130:131], v[246:247]
	v_pk_fma_f32 v[48:49], v[158:159], v[232:233], v[246:247]
	v_pk_fma_f32 v[238:239], v[128:129], v[244:245], v[238:239]
	v_pk_fma_f32 v[38:39], v[168:169], v[234:235], v[248:249]
	v_pk_fma_f32 v[238:239], v[132:133], v[248:249], v[238:239]
	v_pk_fma_f32 v[32:33], v[170:171], v[236:237], v[250:251]
	v_pk_fma_f32 v[238:239], v[134:135], v[250:251], v[238:239]
	ds_read_b128 v[156:159], v188 offset:23552
	ds_read_b128 v[168:171], v188 offset:23808
	ds_read_b128 v[128:131], v188 offset:6656
	ds_read_b128 v[132:135], v188 offset:6912
	s_waitcnt lgkmcnt(8)
	v_pk_add_f32 v[230:231], v[184:185], v[36:37] op_sel_hi:[0,1] neg_lo:[0,1] neg_hi:[0,1]
	v_pk_add_f32 v[232:233], v[184:185], v[48:49] op_sel_hi:[0,1] neg_lo:[0,1] neg_hi:[0,1]
	v_pk_add_f32 v[234:235], v[184:185], v[38:39] op_sel_hi:[0,1] neg_lo:[0,1] neg_hi:[0,1]
	v_pk_add_f32 v[236:237], v[184:185], v[32:33] op_sel_hi:[0,1] neg_lo:[0,1] neg_hi:[0,1]
	v_add_f32_e32 v224, v238, v239
	v_pk_fma_f32 v[244:245], v[120:121], v[230:231], v[36:37]
	v_pk_mul_f32 v[240:241], v[150:151], v[48:49]
	v_pk_fma_f32 v[246:247], v[122:123], v[232:233], v[48:49]
	v_pk_fma_f32 v[240:241], v[148:149], v[36:37], v[240:241]
	v_pk_fma_f32 v[248:249], v[124:125], v[234:235], v[38:39]
	v_pk_fma_f32 v[240:241], v[152:153], v[38:39], v[240:241]
	v_pk_fma_f32 v[250:251], v[126:127], v[236:237], v[32:33]
	v_pk_fma_f32 v[240:241], v[154:155], v[32:33], v[240:241]
	ds_read_b128 v[120:123], v188 offset:24064
	ds_read_b128 v[124:127], v188 offset:24320
	ds_read_b128 v[148:151], v188 offset:7168
	ds_read_b128 v[152:155], v188 offset:7424
	s_waitcnt lgkmcnt(8)
	v_pk_add_f32 v[230:231], v[184:185], v[244:245] op_sel:[1,0] op_sel_hi:[1,1] neg_lo:[0,1] neg_hi:[0,1]
	v_pk_add_f32 v[232:233], v[184:185], v[246:247] op_sel:[1,0] op_sel_hi:[1,1] neg_lo:[0,1] neg_hi:[0,1]
	v_pk_add_f32 v[234:235], v[184:185], v[248:249] op_sel:[1,0] op_sel_hi:[1,1] neg_lo:[0,1] neg_hi:[0,1]
	v_pk_add_f32 v[236:237], v[184:185], v[250:251] op_sel:[1,0] op_sel_hi:[1,1] neg_lo:[0,1] neg_hi:[0,1]
	v_add_f32_e32 v225, v240, v241
	v_pk_fma_f32 v[36:37], v[136:137], v[230:231], v[244:245]
	v_pk_mul_f32 v[238:239], v[114:115], v[246:247]
	v_pk_fma_f32 v[48:49], v[138:139], v[232:233], v[246:247]
	v_pk_fma_f32 v[238:239], v[112:113], v[244:245], v[238:239]
	v_pk_fma_f32 v[38:39], v[144:145], v[234:235], v[248:249]
	v_pk_fma_f32 v[238:239], v[116:117], v[248:249], v[238:239]
	v_pk_fma_f32 v[32:33], v[146:147], v[236:237], v[250:251]
	v_pk_fma_f32 v[238:239], v[118:119], v[250:251], v[238:239]
	ds_read_b128 v[112:115], v188 offset:7680
	ds_read_b128 v[116:119], v188 offset:7936
	s_waitcnt lgkmcnt(6)
	v_pk_add_f32 v[230:231], v[186:187], v[36:37] op_sel_hi:[0,1] neg_lo:[0,1] neg_hi:[0,1]
	v_pk_add_f32 v[232:233], v[186:187], v[48:49] op_sel_hi:[0,1] neg_lo:[0,1] neg_hi:[0,1]
	v_pk_add_f32 v[234:235], v[186:187], v[38:39] op_sel_hi:[0,1] neg_lo:[0,1] neg_hi:[0,1]
	v_pk_add_f32 v[236:237], v[186:187], v[32:33] op_sel_hi:[0,1] neg_lo:[0,1] neg_hi:[0,1]
	v_add_f32_e32 v226, v238, v239
	v_pk_fma_f32 v[244:245], v[156:157], v[230:231], v[36:37]
	v_pk_mul_f32 v[240:241], v[130:131], v[48:49]
	v_pk_fma_f32 v[246:247], v[158:159], v[232:233], v[48:49]
	v_pk_fma_f32 v[240:241], v[128:129], v[36:37], v[240:241]
	v_pk_fma_f32 v[248:249], v[168:169], v[234:235], v[38:39]
	v_pk_fma_f32 v[240:241], v[132:133], v[38:39], v[240:241]
	v_pk_fma_f32 v[250:251], v[170:171], v[236:237], v[32:33]
	v_pk_fma_f32 v[240:241], v[134:135], v[32:33], v[240:241]
	s_waitcnt lgkmcnt(2)
	v_pk_add_f32 v[230:231], v[186:187], v[244:245] op_sel:[1,0] op_sel_hi:[1,1] neg_lo:[0,1] neg_hi:[0,1]
	v_pk_add_f32 v[232:233], v[186:187], v[246:247] op_sel:[1,0] op_sel_hi:[1,1] neg_lo:[0,1] neg_hi:[0,1]
	v_pk_add_f32 v[234:235], v[186:187], v[248:249] op_sel:[1,0] op_sel_hi:[1,1] neg_lo:[0,1] neg_hi:[0,1]
	v_pk_add_f32 v[236:237], v[186:187], v[250:251] op_sel:[1,0] op_sel_hi:[1,1] neg_lo:[0,1] neg_hi:[0,1]
	v_add_f32_e32 v227, v240, v241
	v_pk_fma_f32 v[36:37], v[120:121], v[230:231], v[244:245]
	v_pk_mul_f32 v[238:239], v[150:151], v[246:247]
	v_pk_fma_f32 v[48:49], v[122:123], v[232:233], v[246:247]
	v_pk_fma_f32 v[238:239], v[148:149], v[244:245], v[238:239]
	v_pk_fma_f32 v[38:39], v[124:125], v[234:235], v[248:249]
	v_pk_fma_f32 v[238:239], v[152:153], v[248:249], v[238:239]
	v_pk_fma_f32 v[32:33], v[126:127], v[236:237], v[250:251]
	v_pk_fma_f32 v[238:239], v[154:155], v[250:251], v[238:239]
	s_waitcnt lgkmcnt(0)
	v_add_f32_e32 v228, v238, v239
	v_pk_mul_f32 v[240:241], v[114:115], v[48:49]
	v_add_f32_dpp v214, v214, v214 row_mirror row_mask:0xf bank_mask:0x3 bound_ctrl:1
	v_pk_fma_f32 v[240:241], v[112:113], v[36:37], v[240:241]
	v_add_f32_dpp v214, v222, v222 row_mirror row_mask:0xf bank_mask:0xc bound_ctrl:1
	v_pk_fma_f32 v[240:241], v[116:117], v[38:39], v[240:241]
	v_add_f32_dpp v215, v215, v215 row_mirror row_mask:0xf bank_mask:0x3 bound_ctrl:1
	v_pk_fma_f32 v[240:241], v[118:119], v[32:33], v[240:241]
	v_add_f32_dpp v215, v223, v223 row_mirror row_mask:0xf bank_mask:0xc bound_ctrl:1
	v_add_f32_e32 v229, v240, v241
	v_add_f32_dpp v216, v216, v216 row_mirror row_mask:0xf bank_mask:0x3 bound_ctrl:1
	v_add_f32_dpp v216, v224, v224 row_mirror row_mask:0xf bank_mask:0xc bound_ctrl:1
	v_add_f32_dpp v217, v217, v217 row_mirror row_mask:0xf bank_mask:0x3 bound_ctrl:1
	v_add_f32_dpp v217, v225, v225 row_mirror row_mask:0xf bank_mask:0xc bound_ctrl:1
	v_add_f32_dpp v218, v218, v218 row_mirror row_mask:0xf bank_mask:0x3 bound_ctrl:1
	v_add_f32_dpp v218, v226, v226 row_mirror row_mask:0xf bank_mask:0xc bound_ctrl:1
	v_add_f32_dpp v219, v219, v219 row_mirror row_mask:0xf bank_mask:0x3 bound_ctrl:1
	v_add_f32_dpp v219, v227, v227 row_mirror row_mask:0xf bank_mask:0xc bound_ctrl:1
	v_add_f32_dpp v220, v220, v220 row_mirror row_mask:0xf bank_mask:0x3 bound_ctrl:1
	v_add_f32_dpp v220, v228, v228 row_mirror row_mask:0xf bank_mask:0xc bound_ctrl:1
	v_add_f32_dpp v221, v221, v221 row_mirror row_mask:0xf bank_mask:0x3 bound_ctrl:1
	v_add_f32_dpp v221, v229, v229 row_mirror row_mask:0xf bank_mask:0xc bound_ctrl:1
	v_add_f32_dpp v214, v214, v214 row_half_mirror row_mask:0xf bank_mask:0x5 bound_ctrl:1
	v_add_f32_dpp v214, v218, v218 row_half_mirror row_mask:0xf bank_mask:0xa bound_ctrl:1
	v_add_f32_dpp v215, v215, v215 row_half_mirror row_mask:0xf bank_mask:0x5 bound_ctrl:1
	v_add_f32_dpp v215, v219, v219 row_half_mirror row_mask:0xf bank_mask:0xa bound_ctrl:1
	v_add_f32_dpp v216, v216, v216 row_half_mirror row_mask:0xf bank_mask:0x5 bound_ctrl:1
	v_add_f32_dpp v216, v220, v220 row_half_mirror row_mask:0xf bank_mask:0xa bound_ctrl:1
	v_add_f32_dpp v217, v217, v217 row_half_mirror row_mask:0xf bank_mask:0x5 bound_ctrl:1
	v_add_f32_dpp v217, v221, v221 row_half_mirror row_mask:0xf bank_mask:0xa bound_ctrl:1
	v_add_f32_dpp v192, v214, v214 quad_perm:[2,3,0,1] row_mask:0xf bank_mask:0xf bound_ctrl:1
	v_add_f32_dpp v193, v216, v216 quad_perm:[2,3,0,1] row_mask:0xf bank_mask:0xf bound_ctrl:1
	v_add_f32_dpp v194, v215, v215 quad_perm:[2,3,0,1] row_mask:0xf bank_mask:0xf bound_ctrl:1
	v_add_f32_dpp v195, v217, v217 quad_perm:[2,3,0,1] row_mask:0xf bank_mask:0xf bound_ctrl:1
	v_cndmask_b32_e64 v214, v193, v192, s[42:43]
	v_cndmask_b32_e64 v215, v195, v194, s[42:43]
	s_nop 0
	v_add_f32_dpp v192, v214, v214 quad_perm:[1,0,3,2] row_mask:0xf bank_mask:0xf bound_ctrl:1
	v_add_f32_dpp v193, v215, v215 quad_perm:[1,0,3,2] row_mask:0xf bank_mask:0xf bound_ctrl:1
	v_or_b32_e32 v24, s25, v26
	s_and_b64 vcc, exec, s[0:1]
	v_cndmask_b32_e64 v25, v193, v192, s[44:45]
	s_cbranch_vccz .LBB0_218
	s_mov_b64 s[36:37], -1
	s_and_b64 vcc, exec, s[76:77]
	s_cbranch_vccz .LBB0_222
	v_sub_u32_e32 v91, 0x21ff, v24
	s_mov_b64 s[36:37], 0

.LBB0_224:
	s_waitcnt vmcnt(4)
	v_lshlrev_b32_e32 v28, 16, v8
	v_and_b32_e32 v29, 0xffff0000, v8
	v_lshlrev_b32_e32 v30, 16, v9
	v_and_b32_e32 v31, 0xffff0000, v9
	v_lshlrev_b32_e32 v8, 16, v10
	v_and_b32_e32 v9, 0xffff0000, v10
	v_lshlrev_b32_e32 v10, 16, v11
	v_and_b32_e32 v11, 0xffff0000, v11
	ds_write_b128 v64, v[28:31] offset:36864
	ds_write_b128 v64, v[8:11] offset:37120
	s_waitcnt vmcnt(3)
	v_lshlrev_b32_e32 v8, 16, v4
	v_and_b32_e32 v9, 0xffff0000, v4
	v_lshlrev_b32_e32 v10, 16, v5
	v_and_b32_e32 v11, 0xffff0000, v5
	v_lshlrev_b32_e32 v4, 16, v6
	v_and_b32_e32 v5, 0xffff0000, v6
	v_lshlrev_b32_e32 v6, 16, v7
	v_and_b32_e32 v7, 0xffff0000, v7
	ds_write_b128 v64, v[8:11] offset:53248
	ds_write_b128 v64, v[4:7] offset:53504
	s_and_saveexec_b64 s[30:31], s[38:39]
	s_cbranch_execz .LBB0_226
	v_lshlrev_b32_e32 v4, 16, v0
	v_and_b32_e32 v5, 0xffff0000, v0
	v_lshlrev_b32_e32 v6, 16, v1
	v_and_b32_e32 v7, 0xffff0000, v1
	v_lshlrev_b32_e32 v8, 16, v2
	v_and_b32_e32 v9, 0xffff0000, v2
	v_lshlrev_b32_e32 v10, 16, v3
	v_and_b32_e32 v11, 0xffff0000, v3
	ds_write_b128 v73, v[4:7]
	ds_write_b128 v73, v[8:11] offset:16

.LBB0_242:
	v_cvt_pk_bf16_f32 v26, v25, s0
	v_ashrrev_i32_e32 v25, 31, v24
	v_lshl_add_u64 v[24:25], s[40:41], 0, v[24:25]
	s_xor_b64 s[24:25], s[74:75], -1
	v_lshlrev_b64 v[24:25], 11, v[24:25]
	v_lshl_add_u64 v[24:25], v[46:47], 0, v[24:25]
	s_mov_b32 s30, 16
	s_mov_b64 s[74:75], 0
	s_and_b64 vcc, exec, s[24:25]
	global_store_short v[24:25], v26, off
	s_cbranch_vccnz .LBB0_248
.LBB0_243:
	v_lshl_add_u32 v188, s30, 9, v69
	v_lshl_add_u32 v189, s30, 7, v72
	v_add_u32_e32 v190, 0x11400, v189
	v_add_u32_e32 v189, 0x11000, v189
	ds_read2_b32 v[172:173], v189 offset1:32
	ds_read2_b32 v[174:175], v189 offset0:64 offset1:96
	ds_read2_b32 v[176:177], v189 offset0:128 offset1:160
	ds_read2_b32 v[178:179], v189 offset0:192 offset1:224
	ds_read_b128 v[120:123], v188 offset:53248
	ds_read_b128 v[124:127], v188 offset:53504
	ds_read_b128 v[112:115], v188 offset:36864
	ds_read_b128 v[116:119], v188 offset:37120
	ds_read_b128 v[136:139], v188 offset:53760
	ds_read_b128 v[144:147], v188 offset:54016
	ds_read_b128 v[156:159], v188 offset:54272
	ds_read_b128 v[168:171], v188 offset:54528
	ds_read_b128 v[128:131], v188 offset:37376
	ds_read_b128 v[132:135], v188 offset:37632
	s_waitcnt lgkmcnt(8)
	v_pk_add_f32 v[230:231], v[172:173], v[36:37] op_sel_hi:[0,1] neg_lo:[0,1] neg_hi:[0,1]
	v_pk_add_f32 v[232:233], v[172:173], v[48:49] op_sel_hi:[0,1] neg_lo:[0,1] neg_hi:[0,1]
	v_pk_add_f32 v[234:235], v[172:173], v[38:39] op_sel_hi:[0,1] neg_lo:[0,1] neg_hi:[0,1]
	v_pk_add_f32 v[236:237], v[172:173], v[32:33] op_sel_hi:[0,1] neg_lo:[0,1] neg_hi:[0,1]
	v_pk_fma_f32 v[244:245], v[120:121], v[230:231], v[36:37]
	v_pk_fma_f32 v[246:247], v[122:123], v[232:233], v[48:49]
	v_pk_fma_f32 v[248:249], v[124:125], v[234:235], v[38:39]
	v_pk_fma_f32 v[250:251], v[126:127], v[236:237], v[32:33]
	ds_read_b128 v[120:123], v188 offset:54784
	ds_read_b128 v[124:127], v188 offset:55040
	ds_read_b128 v[148:151], v188 offset:37888
	ds_read_b128 v[152:155], v188 offset:38144
	s_waitcnt lgkmcnt(8)
	v_pk_add_f32 v[230:231], v[172:173], v[244:245] op_sel:[1,0] op_sel_hi:[1,1] neg_lo:[0,1] neg_hi:[0,1]
	v_pk_add_f32 v[232:233], v[172:173], v[246:247] op_sel:[1,0] op_sel_hi:[1,1] neg_lo:[0,1] neg_hi:[0,1]
	v_pk_add_f32 v[234:235], v[172:173], v[248:249] op_sel:[1,0] op_sel_hi:[1,1] neg_lo:[0,1] neg_hi:[0,1]
	v_pk_add_f32 v[236:237], v[172:173], v[250:251] op_sel:[1,0] op_sel_hi:[1,1] neg_lo:[0,1] neg_hi:[0,1]
	v_pk_fma_f32 v[36:37], v[136:137], v[230:231], v[244:245]
	v_pk_mul_f32 v[238:239], v[114:115], v[246:247]
	v_pk_fma_f32 v[48:49], v[138:139], v[232:233], v[246:247]
	v_pk_fma_f32 v[238:239], v[112:113], v[244:245], v[238:239]
	v_pk_fma_f32 v[38:39], v[144:145], v[234:235], v[248:249]
	v_pk_fma_f32 v[238:239], v[116:117], v[248:249], v[238:239]
	v_pk_fma_f32 v[32:33], v[146:147], v[236:237], v[250:251]
	v_pk_fma_f32 v[238:239], v[118:119], v[250:251], v[238:239]
	ds_read_b128 v[136:139], v188 offset:55296
	ds_read_b128 v[144:147], v188 offset:55552
	ds_read_b128 v[112:115], v188 offset:38400
	ds_read_b128 v[116:119], v188 offset:38656
	s_waitcnt lgkmcnt(8)
	v_pk_add_f32 v[230:231], v[174:175], v[36:37] op_sel_hi:[0,1] neg_lo:[0,1] neg_hi:[0,1]
	v_pk_add_f32 v[232:233], v[174:175], v[48:49] op_sel_hi:[0,1] neg_lo:[0,1] neg_hi:[0,1]
	v_pk_add_f32 v[234:235], v[174:175], v[38:39] op_sel_hi:[0,1] neg_lo:[0,1] neg_hi:[0,1]
	v_pk_add_f32 v[236:237], v[174:175], v[32:33] op_sel_hi:[0,1] neg_lo:[0,1] neg_hi:[0,1]
	v_add_f32_e32 v214, v238, v239
	v_pk_fma_f32 v[244:245], v[156:157], v[230:231], v[36:37]
	v_pk_mul_f32 v[240:241], v[130:131], v[48:49]
	v_pk_fma_f32 v[246:247], v[158:159], v[232:233], v[48:49]
	v_pk_fma_f32 v[240:241], v[128:129], v[36:37], v[240:241]
	v_pk_fma_f32 v[248:249], v[168:169], v[234:235], v[38:39]
	v_pk_fma_f32 v[240:241], v[132:133], v[38:39], v[240:241]
	v_pk_fma_f32 v[250:251], v[170:171], v[236:237], v[32:33]
	v_pk_fma_f32 v[240:241], v[134:135], v[32:33], v[240:241]
	ds_read_b128 v[156:159], v188 offset:55808
	ds_read_b128 v[168:171], v188 offset:56064
	ds_read_b128 v[128:131], v188 offset:38912
	ds_read_b128 v[132:135], v188 offset:39168
	s_waitcnt lgkmcnt(8)
	v_pk_add_f32 v[230:231], v[174:175], v[244:245] op_sel:[1,0] op_sel_hi:[1,1] neg_lo:[0,1] neg_hi:[0,1]
	v_pk_add_f32 v[232:233], v[174:175], v[246:247] op_sel:[1,0] op_sel_hi:[1,1] neg_lo:[0,1] neg_hi:[0,1]
	v_pk_add_f32 v[234:235], v[174:175], v[248:249] op_sel:[1,0] op_sel_hi:[1,1] neg_lo:[0,1] neg_hi:[0,1]
	v_pk_add_f32 v[236:237], v[174:175], v[250:251] op_sel:[1,0] op_sel_hi:[1,1] neg_lo:[0,1] neg_hi:[0,1]
	v_add_f32_e32 v215, v240, v241
	v_pk_fma_f32 v[36:37], v[120:121], v[230:231], v[244:245]
	v_pk_mul_f32 v[238:239], v[150:151], v[246:247]
	v_pk_fma_f32 v[48:49], v[122:123], v[232:233], v[246:247]
	v_pk_fma_f32 v[238:239], v[148:149], v[244:245], v[238:239]
	v_pk_fma_f32 v[38:39], v[124:125], v[234:235], v[248:249]
	v_pk_fma_f32 v[238:239], v[152:153], v[248:249], v[238:239]
	v_pk_fma_f32 v[32:33], v[126:127], v[236:237], v[250:251]
	v_pk_fma_f32 v[238:239], v[154:155], v[250:251], v[238:239]
	ds_read_b128 v[120:123], v188 offset:56320
	ds_read_b128 v[124:127], v188 offset:56576
	ds_read_b128 v[148:151], v188 offset:39424
	ds_read_b128 v[152:155], v188 offset:39680
	ds_read2_b32 v[180:181], v190 offset1:32
	ds_read2_b32 v[182:183], v190 offset0:64 offset1:96
	ds_read2_b32 v[184:185], v190 offset0:128 offset1:160
	ds_read2_b32 v[186:187], v190 offset0:192 offset1:224
	s_waitcnt lgkmcnt(12)
	v_pk_add_f32 v[230:231], v[176:177], v[36:37] op_sel_hi:[0,1] neg_lo:[0,1] neg_hi:[0,1]
	v_pk_add_f32 v[232:233], v[176:177], v[48:49] op_sel_hi:[0,1] neg_lo:[0,1] neg_hi:[0,1]
	v_pk_add_f32 v[234:235], v[176:177], v[38:39] op_sel_hi:[0,1] neg_lo:[0,1] neg_hi:[0,1]
	v_pk_add_f32 v[236:237], v[176:177], v[32:33] op_sel_hi:[0,1] neg_lo:[0,1] neg_hi:[0,1]
	v_add_f32_e32 v216, v238, v239
	v_pk_fma_f32 v[244:245], v[136:137], v[230:231], v[36:37]
	v_pk_mul_f32 v[240:241], v[114:115], v[48:49]
	v_pk_fma_f32 v[246:247], v[138:139], v[232:233], v[48:49]
	v_pk_fma_f32 v[240:241], v[112:113], v[36:37], v[240:241]
	v_pk_fma_f32 v[248:249], v[144:145], v[234:235], v[38:39]
	v_pk_fma_f32 v[240:241], v[116:117], v[38:39], v[240:241]
	v_pk_fma_f32 v[250:251], v[146:147], v[236:237], v[32:33]
	v_pk_fma_f32 v[240:241], v[118:119], v[32:33], v[240:241]
	ds_read_b128 v[136:139], v188 offset:56832
	ds_read_b128 v[144:147], v188 offset:57088
	ds_read_b128 v[112:115], v188 offset:39936
	ds_read_b128 v[116:119], v188 offset:40192
	s_waitcnt lgkmcnt(12)
	v_pk_add_f32 v[230:231], v[176:177], v[244:245] op_sel:[1,0] op_sel_hi:[1,1] neg_lo:[0,1] neg_hi:[0,1]
	v_pk_add_f32 v[232:233], v[176:177], v[246:247] op_sel:[1,0] op_sel_hi:[1,1] neg_lo:[0,1] neg_hi:[0,1]
	v_pk_add_f32 v[234:235], v[176:177], v[248:249] op_sel:[1,0] op_sel_hi:[1,1] neg_lo:[0,1] neg_hi:[0,1]
	v_pk_add_f32 v[236:237], v[176:177], v[250:251] op_sel:[1,0] op_sel_hi:[1,1] neg_lo:[0,1] neg_hi:[0,1]
	v_add_f32_e32 v217, v240, v241
	v_pk_fma_f32 v[36:37], v[156:157], v[230:231], v[244:245]
	v_pk_mul_f32 v[238:239], v[130:131], v[246:247]
	v_pk_fma_f32 v[48:49], v[158:159], v[232:233], v[246:247]
	v_pk_fma_f32 v[238:239], v[128:129], v[244:245], v[238:239]
	v_pk_fma_f32 v[38:39], v[168:169], v[234:235], v[248:249]
	v_pk_fma_f32 v[238:239], v[132:133], v[248:249], v[238:239]
	v_pk_fma_f32 v[32:33], v[170:171], v[236:237], v[250:251]
	v_pk_fma_f32 v[238:239], v[134:135], v[250:251], v[238:239]
	ds_read_b128 v[156:159], v188 offset:57344
	ds_read_b128 v[168:171], v188 offset:57600
	ds_read_b128 v[128:131], v188 offset:40448
	ds_read_b128 v[132:135], v188 offset:40704
	s_waitcnt lgkmcnt(12)
	v_pk_add_f32 v[230:231], v[178:179], v[36:37] op_sel_hi:[0,1] neg_lo:[0,1] neg_hi:[0,1]
	v_pk_add_f32 v[232:233], v[178:179], v[48:49] op_sel_hi:[0,1] neg_lo:[0,1] neg_hi:[0,1]
	v_pk_add_f32 v[234:235], v[178:179], v[38:39] op_sel_hi:[0,1] neg_lo:[0,1] neg_hi:[0,1]
	v_pk_add_f32 v[236:237], v[178:179], v[32:33] op_sel_hi:[0,1] neg_lo:[0,1] neg_hi:[0,1]
	v_add_f32_e32 v218, v238, v239
	v_pk_fma_f32 v[244:245], v[120:121], v[230:231], v[36:37]
	v_pk_mul_f32 v[240:241], v[150:151], v[48:49]
	v_pk_fma_f32 v[246:247], v[122:123], v[232:233], v[48:49]
	v_pk_fma_f32 v[240:241], v[148:149], v[36:37], v[240:241]
	v_pk_fma_f32 v[248:249], v[124:125], v[234:235], v[38:39]
	v_pk_fma_f32 v[240:241], v[152:153], v[38:39], v[240:241]
	v_pk_fma_f32 v[250:251], v[126:127], v[236:237], v[32:33]
	v_pk_fma_f32 v[240:241], v[154:155], v[32:33], v[240:241]
	ds_read_b128 v[120:123], v188 offset:57856
	ds_read_b128 v[124:127], v188 offset:58112
	ds_read_b128 v[148:151], v188 offset:40960
	ds_read_b128 v[152:155], v188 offset:41216
	s_waitcnt lgkmcnt(8)
	v_pk_add_f32 v[230:231], v[178:179], v[244:245] op_sel:[1,0] op_sel_hi:[1,1] neg_lo:[0,1] neg_hi:[0,1]
	v_pk_add_f32 v[232:233], v[178:179], v[246:247] op_sel:[1,0] op_sel_hi:[1,1] neg_lo:[0,1] neg_hi:[0,1]
	v_pk_add_f32 v[234:235], v[178:179], v[248:249] op_sel:[1,0] op_sel_hi:[1,1] neg_lo:[0,1] neg_hi:[0,1]
	v_pk_add_f32 v[236:237], v[178:179], v[250:251] op_sel:[1,0] op_sel_hi:[1,1] neg_lo:[0,1] neg_hi:[0,1]
	v_add_f32_e32 v219, v240, v241
	v_pk_fma_f32 v[36:37], v[136:137], v[230:231], v[244:245]
	v_pk_mul_f32 v[238:239], v[114:115], v[246:247]
	v_pk_fma_f32 v[48:49], v[138:139], v[232:233], v[246:247]
	v_pk_fma_f32 v[238:239], v[112:113], v[244:245], v[238:239]
	v_pk_fma_f32 v[38:39], v[144:145], v[234:235], v[248:249]
	v_pk_fma_f32 v[238:239], v[116:117], v[248:249], v[238:239]
	v_pk_fma_f32 v[32:33], v[146:147], v[236:237], v[250:251]
	v_pk_fma_f32 v[238:239], v[118:119], v[250:251], v[238:239]
	ds_read_b128 v[136:139], v188 offset:58368
	ds_read_b128 v[144:147], v188 offset:58624
	ds_read_b128 v[112:115], v188 offset:41472
	ds_read_b128 v[116:119], v188 offset:41728
	s_waitcnt lgkmcnt(8)
	v_pk_add_f32 v[230:231], v[180:181], v[36:37] op_sel_hi:[0,1] neg_lo:[0,1] neg_hi:[0,1]
	v_pk_add_f32 v[232:233], v[180:181], v[48:49] op_sel_hi:[0,1] neg_lo:[0,1] neg_hi:[0,1]
	v_pk_add_f32 v[234:235], v[180:181], v[38:39] op_sel_hi:[0,1] neg_lo:[0,1] neg_hi:[0,1]
	v_pk_add_f32 v[236:237], v[180:181], v[32:33] op_sel_hi:[0,1] neg_lo:[0,1] neg_hi:[0,1]
	v_add_f32_e32 v220, v238, v239
	v_pk_fma_f32 v[244:245], v[156:157], v[230:231], v[36:37]
	v_pk_mul_f32 v[240:241], v[130:131], v[48:49]
	v_pk_fma_f32 v[246:247], v[158:159], v[232:233], v[48:49]
	v_pk_fma_f32 v[240:241], v[128:129], v[36:37], v[240:241]
	v_pk_fma_f32 v[248:249], v[168:169], v[234:235], v[38:39]
	v_pk_fma_f32 v[240:241], v[132:133], v[38:39], v[240:241]
	v_pk_fma_f32 v[250:251], v[170:171], v[236:237], v[32:33]
	v_pk_fma_f32 v[240:241], v[134:135], v[32:33], v[240:241]
	ds_read_b128 v[156:159], v188 offset:58880
	ds_read_b128 v[168:171], v188 offset:59136
	ds_read_b128 v[128:131], v188 offset:41984
	ds_read_b128 v[132:135], v188 offset:42240
	s_waitcnt lgkmcnt(8)
	v_pk_add_f32 v[230:231], v[180:181], v[244:245] op_sel:[1,0] op_sel_hi:[1,1] neg_lo:[0,1] neg_hi:[0,1]
	v_pk_add_f32 v[232:233], v[180:181], v[246:247] op_sel:[1,0] op_sel_hi:[1,1] neg_lo:[0,1] neg_hi:[0,1]
	v_pk_add_f32 v[234:235], v[180:181], v[248:249] op_sel:[1,0] op_sel_hi:[1,1] neg_lo:[0,1] neg_hi:[0,1]
	v_pk_add_f32 v[236:237], v[180:181], v[250:251] op_sel:[1,0] op_sel_hi:[1,1] neg_lo:[0,1] neg_hi:[0,1]
	v_add_f32_e32 v221, v240, v241
	v_pk_fma_f32 v[36:37], v[120:121], v[230:231], v[244:245]
	v_pk_mul_f32 v[238:239], v[150:151], v[246:247]
	v_pk_fma_f32 v[48:49], v[122:123], v[232:233], v[246:247]
	v_pk_fma_f32 v[238:239], v[148:149], v[244:245], v[238:239]
	v_pk_fma_f32 v[38:39], v[124:125], v[234:235], v[248:249]
	v_pk_fma_f32 v[238:239], v[152:153], v[248:249], v[238:239]
	v_pk_fma_f32 v[32:33], v[126:127], v[236:237], v[250:251]
	v_pk_fma_f32 v[238:239], v[154:155], v[250:251], v[238:239]
	ds_read_b128 v[120:123], v188 offset:59392
	ds_read_b128 v[124:127], v188 offset:59648
	ds_read_b128 v[148:151], v188 offset:42496
	ds_read_b128 v[152:155], v188 offset:42752
	s_waitcnt lgkmcnt(8)
	v_pk_add_f32 v[230:231], v[182:183], v[36:37] op_sel_hi:[0,1] neg_lo:[0,1] neg_hi:[0,1]
	v_pk_add_f32 v[232:233], v[182:183], v[48:49] op_sel_hi:[0,1] neg_lo:[0,1] neg_hi:[0,1]
	v_pk_add_f32 v[234:235], v[182:183], v[38:39] op_sel_hi:[0,1] neg_lo:[0,1] neg_hi:[0,1]
	v_pk_add_f32 v[236:237], v[182:183], v[32:33] op_sel_hi:[0,1] neg_lo:[0,1] neg_hi:[0,1]
	v_add_f32_e32 v222, v238, v239
	v_pk_fma_f32 v[244:245], v[136:137], v[230:231], v[36:37]
	v_pk_mul_f32 v[240:241], v[114:115], v[48:49]
	v_pk_fma_f32 v[246:247], v[138:139], v[232:233], v[48:49]
	v_pk_fma_f32 v[240:241], v[112:113], v[36:37], v[240:241]
	v_pk_fma_f32 v[248:249], v[144:145], v[234:235], v[38:39]
	v_pk_fma_f32 v[240:241], v[116:117], v[38:39], v[240:241]
	v_pk_fma_f32 v[250:251], v[146:147], v[236:237], v[32:33]
	v_pk_fma_f32 v[240:241], v[118:119], v[32:33], v[240:241]
	ds_read_b128 v[136:139], v188 offset:59904
	ds_read_b128 v[144:147], v188 offset:60160
	ds_read_b128 v[112:115], v188 offset:43008
	ds_read_b128 v[116:119], v188 offset:43264
	s_waitcnt lgkmcnt(8)
	v_pk_add_f32 v[230:231], v[182:183], v[244:245] op_sel:[1,0] op_sel_hi:[1,1] neg_lo:[0,1] neg_hi:[0,1]
	v_pk_add_f32 v[232:233], v[182:183], v[246:247] op_sel:[1,0] op_sel_hi:[1,1] neg_lo:[0,1] neg_hi:[0,1]
	v_pk_add_f32 v[234:235], v[182:183], v[248:249] op_sel:[1,0] op_sel_hi:[1,1] neg_lo:[0,1] neg_hi:[0,1]
	v_pk_add_f32 v[236:237], v[182:183], v[250:251] op_sel:[1,0] op_sel_hi:[1,1] neg_lo:[0,1] neg_hi:[0,1]
	v_add_f32_e32 v223, v240, v241
	v_pk_fma_f32 v[36:37], v[156:157], v[230:231], v[244:245]
	v_pk_mul_f32 v[238:239], v[130:131], v[246:247]
	v_pk_fma_f32 v[48:49], v[158:159], v[232:233], v[246:247]
	v_pk_fma_f32 v[238:239], v[128:129], v[244:245], v[238:239]
	v_pk_fma_f32 v[38:39], v[168:169], v[234:235], v[248:249]
	v_pk_fma_f32 v[238:239], v[132:133], v[248:249], v[238:239]
	v_pk_fma_f32 v[32:33], v[170:171], v[236:237], v[250:251]
	v_pk_fma_f32 v[238:239], v[134:135], v[250:251], v[238:239]
	ds_read_b128 v[156:159], v188 offset:60416
	ds_read_b128 v[168:171], v188 offset:60672
	ds_read_b128 v[128:131], v188 offset:43520
	ds_read_b128 v[132:135], v188 offset:43776
	s_waitcnt lgkmcnt(8)
	v_pk_add_f32 v[230:231], v[184:185], v[36:37] op_sel_hi:[0,1] neg_lo:[0,1] neg_hi:[0,1]
	v_pk_add_f32 v[232:233], v[184:185], v[48:49] op_sel_hi:[0,1] neg_lo:[0,1] neg_hi:[0,1]
	v_pk_add_f32 v[234:235], v[184:185], v[38:39] op_sel_hi:[0,1] neg_lo:[0,1] neg_hi:[0,1]
	v_pk_add_f32 v[236:237], v[184:185], v[32:33] op_sel_hi:[0,1] neg_lo:[0,1] neg_hi:[0,1]
	v_add_f32_e32 v224, v238, v239
	v_pk_fma_f32 v[244:245], v[120:121], v[230:231], v[36:37]
	v_pk_mul_f32 v[240:241], v[150:151], v[48:49]
	v_pk_fma_f32 v[246:247], v[122:123], v[232:233], v[48:49]
	v_pk_fma_f32 v[240:241], v[148:149], v[36:37], v[240:241]
	v_pk_fma_f32 v[248:249], v[124:125], v[234:235], v[38:39]
	v_pk_fma_f32 v[240:241], v[152:153], v[38:39], v[240:241]
	v_pk_fma_f32 v[250:251], v[126:127], v[236:237], v[32:33]
	v_pk_fma_f32 v[240:241], v[154:155], v[32:33], v[240:241]
	ds_read_b128 v[120:123], v188 offset:60928
	ds_read_b128 v[124:127], v188 offset:61184
	ds_read_b128 v[148:151], v188 offset:44032
	ds_read_b128 v[152:155], v188 offset:44288
	s_waitcnt lgkmcnt(8)
	v_pk_add_f32 v[230:231], v[184:185], v[244:245] op_sel:[1,0] op_sel_hi:[1,1] neg_lo:[0,1] neg_hi:[0,1]
	v_pk_add_f32 v[232:233], v[184:185], v[246:247] op_sel:[1,0] op_sel_hi:[1,1] neg_lo:[0,1] neg_hi:[0,1]
	v_pk_add_f32 v[234:235], v[184:185], v[248:249] op_sel:[1,0] op_sel_hi:[1,1] neg_lo:[0,1] neg_hi:[0,1]
	v_pk_add_f32 v[236:237], v[184:185], v[250:251] op_sel:[1,0] op_sel_hi:[1,1] neg_lo:[0,1] neg_hi:[0,1]
	v_add_f32_e32 v225, v240, v241
	v_pk_fma_f32 v[36:37], v[136:137], v[230:231], v[244:245]
	v_pk_mul_f32 v[238:239], v[114:115], v[246:247]
	v_pk_fma_f32 v[48:49], v[138:139], v[232:233], v[246:247]
	v_pk_fma_f32 v[238:239], v[112:113], v[244:245], v[238:239]
	v_pk_fma_f32 v[38:39], v[144:145], v[234:235], v[248:249]
	v_pk_fma_f32 v[238:239], v[116:117], v[248:249], v[238:239]
	v_pk_fma_f32 v[32:33], v[146:147], v[236:237], v[250:251]
	v_pk_fma_f32 v[238:239], v[118:119], v[250:251], v[238:239]
	ds_read_b128 v[112:115], v188 offset:44544
	ds_read_b128 v[116:119], v188 offset:44800
	s_waitcnt lgkmcnt(6)
	v_pk_add_f32 v[230:231], v[186:187], v[36:37] op_sel_hi:[0,1] neg_lo:[0,1] neg_hi:[0,1]
	v_pk_add_f32 v[232:233], v[186:187], v[48:49] op_sel_hi:[0,1] neg_lo:[0,1] neg_hi:[0,1]
	v_pk_add_f32 v[234:235], v[186:187], v[38:39] op_sel_hi:[0,1] neg_lo:[0,1] neg_hi:[0,1]
	v_pk_add_f32 v[236:237], v[186:187], v[32:33] op_sel_hi:[0,1] neg_lo:[0,1] neg_hi:[0,1]
	v_add_f32_e32 v226, v238, v239
	v_pk_fma_f32 v[244:245], v[156:157], v[230:231], v[36:37]
	v_pk_mul_f32 v[240:241], v[130:131], v[48:49]
	v_pk_fma_f32 v[246:247], v[158:159], v[232:233], v[48:49]
	v_pk_fma_f32 v[240:241], v[128:129], v[36:37], v[240:241]
	v_pk_fma_f32 v[248:249], v[168:169], v[234:235], v[38:39]
	v_pk_fma_f32 v[240:241], v[132:133], v[38:39], v[240:241]
	v_pk_fma_f32 v[250:251], v[170:171], v[236:237], v[32:33]
	v_pk_fma_f32 v[240:241], v[134:135], v[32:33], v[240:241]
	s_waitcnt lgkmcnt(2)
	v_pk_add_f32 v[230:231], v[186:187], v[244:245] op_sel:[1,0] op_sel_hi:[1,1] neg_lo:[0,1] neg_hi:[0,1]
	v_pk_add_f32 v[232:233], v[186:187], v[246:247] op_sel:[1,0] op_sel_hi:[1,1] neg_lo:[0,1] neg_hi:[0,1]
	v_pk_add_f32 v[234:235], v[186:187], v[248:249] op_sel:[1,0] op_sel_hi:[1,1] neg_lo:[0,1] neg_hi:[0,1]
	v_pk_add_f32 v[236:237], v[186:187], v[250:251] op_sel:[1,0] op_sel_hi:[1,1] neg_lo:[0,1] neg_hi:[0,1]
	v_add_f32_e32 v227, v240, v241
	v_pk_fma_f32 v[36:37], v[120:121], v[230:231], v[244:245]
	v_pk_mul_f32 v[238:239], v[150:151], v[246:247]
	v_pk_fma_f32 v[48:49], v[122:123], v[232:233], v[246:247]
	v_pk_fma_f32 v[238:239], v[148:149], v[244:245], v[238:239]
	v_pk_fma_f32 v[38:39], v[124:125], v[234:235], v[248:249]
	v_pk_fma_f32 v[238:239], v[152:153], v[248:249], v[238:239]
	v_pk_fma_f32 v[32:33], v[126:127], v[236:237], v[250:251]
	v_pk_fma_f32 v[238:239], v[154:155], v[250:251], v[238:239]
	s_waitcnt lgkmcnt(0)
	v_add_f32_e32 v228, v238, v239
	v_pk_mul_f32 v[240:241], v[114:115], v[48:49]
	v_add_f32_dpp v214, v214, v214 row_mirror row_mask:0xf bank_mask:0x3 bound_ctrl:1
	v_pk_fma_f32 v[240:241], v[112:113], v[36:37], v[240:241]
	v_add_f32_dpp v214, v222, v222 row_mirror row_mask:0xf bank_mask:0xc bound_ctrl:1
	v_pk_fma_f32 v[240:241], v[116:117], v[38:39], v[240:241]
	v_add_f32_dpp v215, v215, v215 row_mirror row_mask:0xf bank_mask:0x3 bound_ctrl:1
	v_pk_fma_f32 v[240:241], v[118:119], v[32:33], v[240:241]
	v_add_f32_dpp v215, v223, v223 row_mirror row_mask:0xf bank_mask:0xc bound_ctrl:1
	v_add_f32_e32 v229, v240, v241
	v_add_f32_dpp v216, v216, v216 row_mirror row_mask:0xf bank_mask:0x3 bound_ctrl:1
	v_add_f32_dpp v216, v224, v224 row_mirror row_mask:0xf bank_mask:0xc bound_ctrl:1
	v_add_f32_dpp v217, v217, v217 row_mirror row_mask:0xf bank_mask:0x3 bound_ctrl:1
	v_add_f32_dpp v217, v225, v225 row_mirror row_mask:0xf bank_mask:0xc bound_ctrl:1
	v_add_f32_dpp v218, v218, v218 row_mirror row_mask:0xf bank_mask:0x3 bound_ctrl:1
	v_add_f32_dpp v218, v226, v226 row_mirror row_mask:0xf bank_mask:0xc bound_ctrl:1
	v_add_f32_dpp v219, v219, v219 row_mirror row_mask:0xf bank_mask:0x3 bound_ctrl:1
	v_add_f32_dpp v219, v227, v227 row_mirror row_mask:0xf bank_mask:0xc bound_ctrl:1
	v_add_f32_dpp v220, v220, v220 row_mirror row_mask:0xf bank_mask:0x3 bound_ctrl:1
	v_add_f32_dpp v220, v228, v228 row_mirror row_mask:0xf bank_mask:0xc bound_ctrl:1
	v_add_f32_dpp v221, v221, v221 row_mirror row_mask:0xf bank_mask:0x3 bound_ctrl:1
	v_add_f32_dpp v221, v229, v229 row_mirror row_mask:0xf bank_mask:0xc bound_ctrl:1
	v_add_f32_dpp v214, v214, v214 row_half_mirror row_mask:0xf bank_mask:0x5 bound_ctrl:1
	v_add_f32_dpp v214, v218, v218 row_half_mirror row_mask:0xf bank_mask:0xa bound_ctrl:1
	v_add_f32_dpp v215, v215, v215 row_half_mirror row_mask:0xf bank_mask:0x5 bound_ctrl:1
	v_add_f32_dpp v215, v219, v219 row_half_mirror row_mask:0xf bank_mask:0xa bound_ctrl:1
	v_add_f32_dpp v216, v216, v216 row_half_mirror row_mask:0xf bank_mask:0x5 bound_ctrl:1
	v_add_f32_dpp v216, v220, v220 row_half_mirror row_mask:0xf bank_mask:0xa bound_ctrl:1
	v_add_f32_dpp v217, v217, v217 row_half_mirror row_mask:0xf bank_mask:0x5 bound_ctrl:1
	v_add_f32_dpp v217, v221, v221 row_half_mirror row_mask:0xf bank_mask:0xa bound_ctrl:1
	v_add_f32_dpp v192, v214, v214 quad_perm:[2,3,0,1] row_mask:0xf bank_mask:0xf bound_ctrl:1
	v_add_f32_dpp v193, v216, v216 quad_perm:[2,3,0,1] row_mask:0xf bank_mask:0xf bound_ctrl:1
	v_add_f32_dpp v194, v215, v215 quad_perm:[2,3,0,1] row_mask:0xf bank_mask:0xf bound_ctrl:1
	v_add_f32_dpp v195, v217, v217 quad_perm:[2,3,0,1] row_mask:0xf bank_mask:0xf bound_ctrl:1
	v_cndmask_b32_e64 v214, v193, v192, s[42:43]
	v_cndmask_b32_e64 v215, v195, v194, s[42:43]
	s_nop 0
	v_add_f32_dpp v192, v214, v214 quad_perm:[1,0,3,2] row_mask:0xf bank_mask:0xf bound_ctrl:1
	v_add_f32_dpp v193, v215, v215 quad_perm:[1,0,3,2] row_mask:0xf bank_mask:0xf bound_ctrl:1
	v_or_b32_e32 v24, s30, v74
	s_and_b64 vcc, exec, s[0:1]
	v_cndmask_b32_e64 v25, v193, v192, s[44:45]
	s_cbranch_vccz .LBB0_242
	s_mov_b64 s[30:31], -1
	s_and_b64 vcc, exec, s[76:77]
	s_cbranch_vccz .LBB0_246
	v_sub_u32_e32 v27, 0x21ff, v24
	s_mov_b64 s[30:31], 0

.LBB0_248:
	s_waitcnt vmcnt(5)
	v_lshlrev_b32_e32 v26, 16, v21
	v_lshlrev_b32_e32 v24, 16, v20
	v_lshlrev_b32_e32 v30, 16, v23
	v_lshlrev_b32_e32 v28, 16, v22
	v_and_b32_e32 v27, 0xffff0000, v21
	v_and_b32_e32 v25, 0xffff0000, v20
	v_and_b32_e32 v31, 0xffff0000, v23
	v_and_b32_e32 v29, 0xffff0000, v22
	ds_write_b128 v64, v[28:31] offset:256
	ds_write_b128 v64, v[24:27]
	s_waitcnt vmcnt(4)
	v_lshlrev_b32_e32 v26, 16, v19
	v_lshlrev_b32_e32 v24, 16, v18
	v_and_b32_e32 v27, 0xffff0000, v19
	v_and_b32_e32 v25, 0xffff0000, v18
	v_lshlrev_b32_e32 v22, 16, v17
	v_lshlrev_b32_e32 v20, 16, v16
	v_and_b32_e32 v23, 0xffff0000, v17
	v_and_b32_e32 v21, 0xffff0000, v16
	ds_write_b128 v64, v[24:27] offset:16640
	ds_write_b128 v64, v[20:23] offset:16384
	s_and_saveexec_b64 s[30:31], s[38:39]
	s_cbranch_execz .LBB0_201
	v_lshlrev_b32_e32 v16, 16, v12
	v_and_b32_e32 v17, 0xffff0000, v12
	v_lshlrev_b32_e32 v18, 16, v13
	v_and_b32_e32 v19, 0xffff0000, v13
	v_lshlrev_b32_e32 v20, 16, v14
	v_and_b32_e32 v21, 0xffff0000, v14
	v_lshlrev_b32_e32 v22, 16, v15
	v_and_b32_e32 v23, 0xffff0000, v15
	ds_write_b128 v65, v[16:19] offset:32768
	ds_write_b128 v65, v[20:23] offset:32784
	s_branch .LBB0_201
